# norm phases: waves that carry a ninth (sample) row are spread over all workgroups (two per workgroup) instead of filling workgroups 0..63
# speedup vs baseline: 1.0140x; 1.0140x over previous
; DI void norm_phase(const float* xp, const float* xs, const float* gvec, const float* MODL  , int sc_off, bf16_t* H, int tid,
;                    const float* P, int nparts, const float* pgate, float* X) {
;     const int lane = tid & 63, gw = blockIdx.x * 8 + (tid >> 6), NGW = gridDim.x * 8;
;     for (int it = gw; it < M; it += NGW) {
;         const int row = it < MS ? MP + it : it - MS;
;         const int bi = batch_of(row);
;         const float* xr = (row < MP ? xp : xs) + (size_t)row * 1024; const float* mr = MODL + (size_t)bi * NMOD;
;         f32x4 v[4]; float ss = 0.f;
; #pragma unroll
;         for (int j = 0; j < 4; ++j) v[j] = *(const f32x4*)(xr + 4 * lane + 256 * j);
; __global__ void __launch_bounds__(512, 2) mega(Args a_unused) {
;     ...
;         } else if (ph == NPHASE - 1) norm_phase(X, X, a->in[32], MOD, 0, nullptr, tid, (const float*)(ws + WS_DYY), 22, MOD + 3 * 6144 + 5120, X);
.LBB0_11:
	s_mov_b64 s[34:35], s[78:79]
	s_mov_b32 s38, s76
	s_mov_b32 s51, s82
	v_mbcnt_lo_u32_b32 v0, -1, 0
	v_mbcnt_hi_u32_b32 v0, -1, v0
	s_mov_b64 s[4:5], -1
	v_add_u32_e32 v194, s90, v0
	s_load_dwordx4 s[24:27], s[34:35], 0x108
	s_mov_b64 s[0:1], 0
	s_mov_b64 s[2:3], 0
	s_waitcnt lgkmcnt(0)
	s_add_u32 s36, s26, 0x7f00000
	s_addc_u32 s37, s27, 0
	s_cmp_lt_i32 s86, 1
	s_cbranch_scc1 .LBB0_19
	s_cmp_gt_i32 s86, 37
	s_cbranch_scc0 .LBB0_132
	s_cmp_eq_u32 s86, 38
	s_mov_b64 s[2:3], -1
	s_cbranch_scc0 .LBB0_131
	v_ashrrev_i32_e32 v0, 6, v194
	v_add_u32_e32 v20, s83, v0
	s_cmpk_lg_i32 s51, 0x100
	s_cbranch_scc1 .Lni_a
	s_lshr_b32 s2, s83, 3
	v_lshl_add_u32 v20, v0, 8, s2
.Lni_a:
	s_movk_i32 s2, 0x4200
	v_cmp_gt_i32_e32 vcc, s2, v20
	s_and_saveexec_b64 s[2:3], vcc
	s_cbranch_execz .LBB0_130
	v_lshlrev_b32_e32 v4, 2, v194
	s_load_dwordx2 s[4:5], s[34:35], 0x100
	v_and_b32_e32 v0, 0xfc, v4
	v_lshlrev_b32_e32 v0, 2, v0
	v_mov_b32_e32 v1, v97
	v_lshl_add_u64 v[2:3], s[26:27], 0, v[0:1]
	s_mov_b64 s[6:7], 0x10d00000
	v_lshl_add_u64 v[22:23], v[2:3], 0, s[6:7]
	s_mov_b64 s[6:7], 0x7f17000
	v_lshl_add_u64 v[24:25], v[2:3], 0, s[6:7]
	v_bfrev_b32_e32 v2, 0.5
	s_movk_i32 s6, 0x80
	v_lshl_add_u64 v[26:27], s[24:25], 0, v[0:1]
	v_bitop3_b32 v50, v4, 4, v2 bitop3:0x6c
	v_bitop3_b32 v51, v4, 8, v2 bitop3:0x6c
	v_bitop3_b32 v52, v4, 16, v2 bitop3:0x6c
	v_bitop3_b32 v53, v4, 32, v2 bitop3:0x6c
	v_bitop3_b32 v54, v4, 64, v2 bitop3:0x6c
	v_bitop3_b32 v55, v4, s6, v2 bitop3:0x6c
	s_waitcnt lgkmcnt(0)
	v_lshl_add_u64 v[28:29], s[4:5], 0, v[0:1]
	v_ashrrev_i32_e32 v21, 31, v20
	s_mov_b64 s[4:5], 0
	s_branch .LBB0_17

; DI void norm_phase(const float* xp, const float* xs, const float* gvec, const float* MODL  , int sc_off, bf16_t* H, int tid,
;                    const float* P, int nparts, const float* pgate, float* X) {
;     const int lane = tid & 63, gw = blockIdx.x * 8 + (tid >> 6), NGW = gridDim.x * 8;
;     for (int it = gw; it < M; it += NGW) {
;         const int row = it < MS ? MP + it : it - MS;
;         const int bi = batch_of(row);
;         const float* xr = (row < MP ? xp : xs) + (size_t)row * 1024; const float* mr = MODL + (size_t)bi * NMOD;
;         f32x4 v[4]; float ss = 0.f;
; #pragma unroll
;         for (int j = 0; j < 4; ++j) v[j] = *(const f32x4*)(xr + 4 * lane + 256 * j);
; __global__ void __launch_bounds__(512, 2) mega(Args a_unused) {
;     ...
;             } else if (k == 6) norm_phase(X, xs, a->in[10] + l * 1024, MOD + l * 6144 + 3072, 1024, H, tid, (const float*)(ws + WS_YC0), 8, MOD + l * 6144 + 2048, X);
.LBB0_225:
	v_ashrrev_i32_e32 v0, 6, v194
	v_add_u32_e32 v16, s83, v0
	s_cmpk_lg_i32 s51, 0x100
	s_cbranch_scc1 .Lni_b
	s_lshr_b32 s2, s83, 3
	v_lshl_add_u32 v16, v0, 8, s2
.Lni_b:
	s_movk_i32 s2, 0x4200
	v_cmp_gt_i32_e32 vcc, s2, v16
	s_and_saveexec_b64 s[2:3], vcc
	s_cbranch_execz .LBB0_230
	v_readlane_b32 s4, v254, 29
	v_readlane_b32 s5, v254, 30
	s_lshl_b64 s[4:5], s[4:5], 2
	s_load_dwordx2 s[8:9], s[34:35], 0x50
	s_add_u32 s6, s36, s4
	s_addc_u32 s7, s37, s5
	v_readlane_b32 s10, v254, 33
	s_add_u32 s4, s6, 0x3000
	v_readlane_b32 s11, v254, 34
	v_lshlrev_b32_e32 v1, 2, v194
	s_addc_u32 s5, s7, 0
	s_lshl_b64 s[10:11], s[10:11], 2
	v_and_b32_e32 v0, 0xfc, v1
	s_waitcnt lgkmcnt(0)
	s_add_u32 s8, s8, s10
	v_lshlrev_b32_e32 v2, 2, v0
	v_mov_b32_e32 v3, v97
	s_addc_u32 s9, s9, s11
	v_lshl_add_u64 v[4:5], s[26:27], 0, v[2:3]
	s_mov_b64 s[10:11], 0x13f00000
	v_lshl_add_u64 v[18:19], v[4:5], 0, s[10:11]
	v_lshl_add_u64 v[4:5], s[6:7], 0, v[2:3]
	s_mov_b64 s[6:7], 0x2000
	v_lshl_add_u64 v[20:21], v[4:5], 0, s[6:7]
	v_bfrev_b32_e32 v4, 0.5
	s_movk_i32 s6, 0x80
	v_lshl_add_u64 v[22:23], s[24:25], 0, v[2:3]
	v_bitop3_b32 v54, v1, 4, v4 bitop3:0x6c
	v_bitop3_b32 v55, v1, 8, v4 bitop3:0x6c
	v_bitop3_b32 v56, v1, 16, v4 bitop3:0x6c
	v_bitop3_b32 v57, v1, 32, v4 bitop3:0x6c
	v_bitop3_b32 v58, v1, 64, v4 bitop3:0x6c
	v_bitop3_b32 v59, v1, s6, v4 bitop3:0x6c
	v_lshl_add_u64 v[24:25], s[8:9], 0, v[2:3]
	v_or_b32_e32 v2, 0x100, v0
	v_or_b32_e32 v4, 0x200, v0
	v_or_b32_e32 v6, 0x300, v0
	v_lshlrev_b32_e32 v8, 1, v0
	v_mov_b32_e32 v9, v97
	v_lshl_add_u64 v[26:27], s[88:89], 0, v[8:9]
	v_ashrrev_i32_e32 v17, 31, v16
	s_mov_b64 s[8:9], 0
	v_lshlrev_b32_e32 v96, 2, v0
	v_lshlrev_b32_e32 v28, 2, v2
	v_lshlrev_b32_e32 v30, 2, v4
	v_lshlrev_b32_e32 v32, 2, v6
	s_branch .LBB0_228

; DI void norm_phase(const float* xp, const float* xs, const float* gvec, const float* MODL  , int sc_off, bf16_t* H, int tid,
;                    const float* P, int nparts, const float* pgate, float* X) {
;     const int lane = tid & 63, gw = blockIdx.x * 8 + (tid >> 6), NGW = gridDim.x * 8;
;     for (int it = gw; it < M; it += NGW) {
;         const int row = it < MS ? MP + it : it - MS;
;         const int bi = batch_of(row);
;         const float* xr = (row < MP ? xp : xs) + (size_t)row * 1024; const float* mr = MODL + (size_t)bi * NMOD;
;         f32x4 v[4]; float ss = 0.f;
; #pragma unroll
;         for (int j = 0; j < 4; ++j) v[j] = *(const f32x4*)(xr + 4 * lane + 256 * j);
; __global__ void __launch_bounds__(512, 2) mega(Args a_unused) {
;     ...
;             if (k == 0) norm_phase(xp, xs, a->in[9] + l * 1024, MOD + l * 6144, 1024, H, tid, (const float*)(ws + WS_DYY), l == 0 ? 0 : 22, MOD + (l - 1) * 6144 + 5120, X);
.LBB0_1949:
	s_and_b64 vcc, exec, s[0:1]
	s_cbranch_vccz .LBB0_1956
	v_ashrrev_i32_e32 v0, 6, v194
	v_add_u32_e32 v20, s83, v0
	s_cmpk_lg_i32 s51, 0x100
	s_cbranch_scc1 .Lni_c
	s_lshr_b32 s0, s83, 3
	v_lshl_add_u32 v20, v0, 8, s0
.Lni_c:
	s_movk_i32 s0, 0x4200
	v_cmp_gt_i32_e32 vcc, s0, v20
	s_and_saveexec_b64 s[0:1], vcc
	v_readlane_b32 s10, v254, 23
	v_readlane_b32 s12, v254, 25
	v_readlane_b32 s11, v254, 24
	v_readlane_b32 s13, v254, 26
	s_cbranch_execz .LBB0_1955
	v_readlane_b32 s4, v254, 29
	v_readlane_b32 s5, v254, 30
	s_lshl_b64 s[2:3], s[4:5], 2
	s_add_u32 s2, s36, s2
	s_addc_u32 s3, s37, s3
	s_addk_i32 s4, 0xe800
	s_load_dwordx2 s[6:7], s[34:35], 0x48
	s_ashr_i32 s5, s4, 31
	s_lshl_b64 s[4:5], s[4:5], 2
	v_readlane_b32 s8, v254, 33
	s_add_u32 s4, s36, s4
	v_readlane_b32 s9, v254, 34
	v_lshlrev_b32_e32 v1, 2, v194
	s_addc_u32 s5, s37, s5
	s_lshl_b64 s[8:9], s[8:9], 2
	v_and_b32_e32 v0, 0xfc, v1
	s_waitcnt lgkmcnt(0)
	s_add_u32 s6, s6, s8
	v_lshlrev_b32_e32 v2, 2, v0
	v_mov_b32_e32 v3, v97
	s_addc_u32 s7, s7, s9
	v_lshl_add_u64 v[4:5], s[26:27], 0, v[2:3]
	s_mov_b64 s[8:9], 0x10d00000
	v_lshl_add_u64 v[22:23], v[4:5], 0, s[8:9]
	v_lshl_add_u64 v[4:5], s[4:5], 0, v[2:3]
	s_mov_b64 s[4:5], 0x5000
	v_lshl_add_u64 v[24:25], v[4:5], 0, s[4:5]
	v_bfrev_b32_e32 v4, 0.5
	s_movk_i32 s4, 0x80
	v_lshl_add_u64 v[26:27], s[24:25], 0, v[2:3]
	v_bitop3_b32 v62, v1, 4, v4 bitop3:0x6c
	v_bitop3_b32 v63, v1, 8, v4 bitop3:0x6c
	v_bitop3_b32 v64, v1, 16, v4 bitop3:0x6c
	v_bitop3_b32 v65, v1, 32, v4 bitop3:0x6c
	v_bitop3_b32 v66, v1, 64, v4 bitop3:0x6c
	v_bitop3_b32 v67, v1, s4, v4 bitop3:0x6c
	v_lshl_add_u64 v[28:29], s[6:7], 0, v[2:3]
	v_or_b32_e32 v2, 0x100, v0
	v_or_b32_e32 v4, 0x200, v0
	v_or_b32_e32 v6, 0x300, v0
	v_lshlrev_b32_e32 v8, 1, v0
	v_mov_b32_e32 v9, v97
	v_lshl_add_u64 v[30:31], s[88:89], 0, v[8:9]
	v_ashrrev_i32_e32 v21, 31, v20
	s_mov_b64 s[4:5], 0
	v_lshlrev_b32_e32 v96, 2, v0
	v_lshlrev_b32_e32 v32, 2, v2
	v_lshlrev_b32_e32 v34, 2, v4
	v_lshlrev_b32_e32 v36, 2, v6
	s_branch .LBB0_1953
